# attention unit prologue: the twelve tile-0 K/Q fragment reads issued together with counted waits (was seven serialized read-wait-MFMA steps); stacked on stack20
# speedup vs baseline: 1.0108x; 1.0108x over previous
; __device__ __forceinline__ bf16_t f2bf(float f) { unsigned u = __float_as_uint(f); return (bf16_t)((u + 0x7fffu + ((u >> 16) & 1u)) >> 16); }
; __device__ __forceinline__ unsigned cvtpk_s(float lo, float hi) { f32x2_t v = {lo, hi}; bf16x2_t b = __builtin_convertvector(v, bf16x2_t); return __builtin_bit_cast(unsigned, b); }
; #define ATT_SB() __builtin_amdgcn_sched_barrier(0)
;     ...
;     { __attribute__((address_space(3))) bf16x8* qst_ = (__attribute__((address_space(3))) bf16x8*)((lds_cptr)shm + LDS_OST + wid * 8192) + lane;
; #pragma unroll
;       for (int d0 = 0; d0 < 4; ++d0) qst_[d0 * 64] = qr[d0]; }
;     const lds_cptr qp = (lds_cptr)shm + LDS_OST + wid * 8192 + lane * 16;
;     ...
;     bf16x8 kaug0, kaug1;
;     { const unsigned sb0 = (unsigned)f2bf((float)r32), sb1 = (unsigned)f2bf((float)(r32 + 32));
;       u32x4 w0 = (u32x4){0x3F803F80u, (sb0 << 16) | 0x3F80u, (sb0 << 16) | sb0, 0u}, w1 = (u32x4){0x3F803F80u, (sb1 << 16) | 0x3F80u, (sb1 << 16) | sb1, 0u};
;       if (hi) { w0 = (u32x4){0u, 0u, 0u, 0u}; w1 = w0; }
;       kaug0 = __builtin_bit_cast(bf16x8, w0); kaug1 = __builtin_bit_cast(bf16x8, w1); }
;     const unsigned w2pos = cvtpk_s(s2, s3), w2neg = cvtpk_s(-s2, -s3), h0pos = cvtpk_s(s1, s2), h0neg = cvtpk_s(-s1, -s2), h1pos = cvtpk_s(s3, 0.f), h1neg = cvtpk_s(-s3, 0.f);
;     float mhatA = 0.f, mhatB = 0.f, lA = 0.f, lB = 0.f;
;     f32x16 oa0 = f32x16{}, oa1 = f32x16{}, ob0 = f32x16{}, ob1 = f32x16{};
;     f32x16 sa0, sa1, sb0, sb1;
;     u32x4 pa0, pa1, pa2, pa3, pb0, pb1, pb2, pb3;
;     bf16x8 qaA, qaB;
;     const lds_cptr shm3 = (lds_cptr)shm;
;     const lds_cptr kp0 = (lds_cptr)shm + LDS_K + (r32 >> 4) * 1024 + (r32 & 15) * 64 + ((hi) ^ ((r32 >> 2) & 3)) * 16;
;     const int koB = (((2 + hi) ^ ((r32 >> 2) & 3)) - ((hi) ^ ((r32 >> 2) & 3))) * 16;
;     const lds_cptr vp0 = shm3 + LDS_V + ((lane >> 4) & 1) * 32 + (lane & 3) * 8 + (4 * hi + ((lane & 15) >> 2)) * 64;
;     const int tq = q0 + wid * 32 + r32;
;     const f32x16 zero = f32x16{};
;     ...
;     ATT_QAUG(ATT_SIDE(d0t)); ATT_KAUG(d0t);
;     ATT_BARV(2);
;     { ATT_DMA(2, 2);
;       const lds_cptr kp = kp0;
;       const bf16x8 ka0 = ATT_KA(0), ka1 = ATT_KA(2048), ka2 = ATT_KB(0), ka3 = ATT_KB(2048), kb0 = ATT_KA(4096), kb1 = ATT_KA(6144), kb2 = ATT_KB(4096), kb3 = ATT_KB(6144);
;       ATT_LDQ();
;       ATT_QKA(); ATT_QKB();
;       ATT_SB(); ATT_BARV(2); ATT_SB();
.LBB0_312:
	s_or_b64 exec, exec, s[36:37]
	s_sub_i32 s15, 8, s15
	v_cvt_f32_u32_e32 v16, s15
	s_lshl_b32 s15, s25, 13
	s_add_i32 s25, s15, 0
	s_mov_b32 s15, 0x3fb8aa3b
	v_exp_f32_e64 v16, -v16
	v_lshlrev_b32_e32 v17, 4, v167
	s_add_i32 s25, s25, 0x11000
	v_add_u32_e32 v174, s25, v17
	v_mul_f32_e32 v18, 0x3fb8aa3b, v16
	v_cvt_pk_bf16_f32 v18, v18, 0
	v_lshlrev_b32_e32 v173, 16, v18
	v_fma_f32 v16, v16, s15, -v173
	v_cvt_pk_bf16_f32 v18, v16, 0
	v_lshlrev_b32_e32 v18, 16, v18
	v_sub_f32_e32 v16, v16, v18
	ds_write_b128 v174, v[0:3]
	ds_write_b128 v174, v[4:7] offset:1024
	ds_write_b128 v174, v[8:11] offset:2048
	ds_write_b128 v174, v[12:15] offset:3072
	v_cvt_f32_ubyte0_e32 v0, v170
	v_cvt_f32_i32_e32 v6, v171
	v_cvt_pk_bf16_f32 v16, v16, 0
	v_bfe_u32 v1, v0, 16, 1
	s_ashr_i32 s22, s17, 7
	v_add_f32_e32 v19, v173, v18
	v_lshlrev_b32_e32 v16, 16, v16
	v_add3_u32 v0, v0, v1, s4
	v_or_b32_e32 v1, 32, v170
	v_add_f32_e32 v92, v19, v16
	v_cvt_f32_ubyte0_e32 v1, v1
	s_cmpk_lt_u32 s17, 0x80
	v_cvt_f32_u32_e32 v5, s21
	v_bfe_u32 v2, v1, 16, 1
	s_cselect_b64 s[40:41], -1, 0
	s_cmp_lt_i32 s22, 1
	v_mul_f32_e32 v182, v92, v6
	v_bfrev_b32_e32 v6, 1
	v_add3_u32 v1, v1, v2, s4
	v_and_b32_e32 v2, 0xffff0000, v0
	s_cselect_b64 s[42:43], -1, 0
	v_cndmask_b32_e64 v6, v182, v6, s[40:41]
	v_or_b32_e32 v3, 0x3f80, v2
	v_or_b32_sdwa v0, v2, v0 dst_sel:DWORD dst_unused:UNUSED_PAD src0_sel:DWORD src1_sel:WORD_1
	v_and_b32_e32 v2, 0xffff0000, v1
	v_cmp_gt_u32_e64 s[38:39], 32, v167
	v_cndmask_b32_e64 v6, -v182, v6, s[42:43]
	v_or_b32_e32 v4, 0x3f80, v2
	v_or_b32_sdwa v1, v2, v1 dst_sel:DWORD dst_unused:UNUSED_PAD src0_sel:DWORD src1_sel:WORD_1
	v_mov_b32_e32 v2, 0x3f803f80
	v_cndmask_b32_e64 v94, 0, v3, s[38:39]
	v_cvt_pk_bf16_f32 v175, v18, v16
	v_xor_b32_e32 v3, 0x80000000, v16
	v_cvt_pk_bf16_f32 v179, v16, 0
	v_lshrrev_b32_e32 v16, 16, v5
	v_and_b32_e32 v5, 0x7fff0000, v5
	v_cvt_pk_bf16_f32 v8, v6, 0
	v_cndmask_b32_e64 v95, 0, v4, s[38:39]
	v_cndmask_b32_e64 v96, 0, v2, s[38:39]
	v_xor_b32_e32 v2, 0x80000000, v18
	v_xor_b32_e32 v4, 0x80000000, v173
	v_or_b32_e32 v5, v16, v5
	v_lshlrev_b32_e32 v8, 16, v8
	v_cndmask_b32_e64 v0, 0, v0, s[38:39]
	v_cvt_pk_bf16_f32 v176, v2, v3
	v_cvt_pk_bf16_f32 v178, v4, v2
	v_lshlrev_b32_e32 v2, 6, v170
	v_lshrrev_b32_e32 v4, 2, v168
	v_sub_f32_e32 v8, v6, v8
	v_cndmask_b32_e64 v130, v5, v96, s[38:39]
	v_cvt_pk_bf16_f32 v180, v3, 0
	v_and_b32_e32 v2, 0x400, v2
	v_lshlrev_b32_e32 v3, 6, v168
	v_bitop3_b32 v52, v169, v4, 3 bitop3:0x78
	v_cvt_pk_bf16_f32 v9, v8, 0
	v_cndmask_b32_e64 v136, 0, v0, s[38:39]
	v_cndmask_b32_e64 v135, v16, v94, s[38:39]
	v_mov_b32_e32 v134, v130
	v_mov_b32_e32 v137, v129
	v_add_u32_e32 v2, 0, v2
	v_and_b32_e32 v3, 0x3c0, v3
	v_lshlrev_b32_e32 v4, 4, v52
	v_cndmask_b32_e64 v7, -v173, 0, s[40:41]
	v_lshlrev_b32_e32 v9, 16, v9
	v_cvt_pk_bf16_f32 v177, v173, v18
	v_add3_u32 v181, v2, v3, v4
	v_cndmask_b32_e64 v2, v176, 0, s[40:41]
	v_cndmask_b32_e64 v3, v178, 0, s[40:41]
	v_cndmask_b32_e64 v4, v180, 0, s[40:41]
	v_cndmask_b32_e64 v7, v173, v7, s[42:43]
	v_sub_f32_e32 v9, v8, v9
	v_cndmask_b32_e64 v1, 0, v1, s[38:39]
	v_cndmask_b32_e64 v2, v175, v2, s[42:43]
	v_cndmask_b32_e64 v3, v177, v3, s[42:43]
	v_cndmask_b32_e64 v4, v179, v4, s[42:43]
	s_cmp_lg_u32 0, -1
	v_cvt_pk_bf16_f32 v6, v6, v8
	v_cvt_pk_bf16_f32 v7, v9, v7
	s_cselect_b32 s15, 0, 0
	v_cndmask_b32_e64 v127, v4, v7, s[38:39]
	v_cndmask_b32_e64 v126, v3, v6, s[38:39]
	v_cndmask_b32_e64 v128, 0, v2, s[38:39]
	v_cndmask_b32_e64 v132, 0, v1, s[38:39]
	v_cndmask_b32_e64 v131, v16, v95, s[38:39]
	v_mov_b32_e32 v133, v129
	s_add_i32 s15, s15, s23
	v_mfma_f32_32x32x16_bf16 v[0:15], v[134:137], v[126:129], 0
	s_waitcnt vmcnt(2) lgkmcnt(0)
	s_barrier
	s_nop 11
	s_mov_b64 s[28:29], 0xa0000
	s_add_i32 s23, s15, 0x4000
	v_lshl_add_u64 v[16:17], v[20:21], 0, s[28:29]
	s_mov_b32 s26, m0
	s_mov_b32 m0, s23
	s_nop 0
	global_load_lds_dwordx4 v[16:17], off
	s_mov_b32 m0, s26
	s_add_i32 s15, s15, 0xc000
	v_lshl_add_u64 v[16:17], v[22:23], 0, s[28:29]
	s_mov_b32 s23, m0
	s_mov_b32 m0, s15
	s_nop 0
	global_load_lds_dwordx4 v[16:17], off
	s_mov_b32 m0, s23
	ds_read_b128 v[48:51], v181
	ds_read_b128 v[74:77], v174
	ds_read_b128 v[78:81], v181 offset:2048
	v_bfe_u32 v97, v168, 2, 2
	v_bitop3_b32 v82, v169, v97, 2 bitop3:0x36
	v_sub_u32_e32 v82, v82, v52
	v_lshlrev_b32_e32 v183, 4, v82
	v_add_u32_e32 v64, v181, v183
	ds_read_b128 v[82:85], v64
	ds_read_b128 v[86:89], v174 offset:1024
	ds_read_b128 v[98:101], v64 offset:2048
	ds_read_b128 v[102:105], v181 offset:4096
	ds_read_b128 v[106:109], v174 offset:2048
	ds_read_b128 v[110:113], v181 offset:6144
	ds_read_b128 v[114:117], v64 offset:4096
	ds_read_b128 v[118:121], v174 offset:3072
	ds_read_b128 v[122:125], v64 offset:6144
	v_mfma_f32_32x32x16_bf16 v[16:31], v[130:133], v[126:129], 0
	v_lshlrev_b32_e32 v172, 2, v169
	s_cmpk_gt_u32 s17, 0x7f
	s_waitcnt lgkmcnt(9)
	v_mfma_f32_32x32x16_bf16 v[32:47], v[48:51], v[74:77], v[0:15]
	v_mfma_f32_32x32x16_bf16 v[48:63], v[78:81], v[74:77], v[16:31]
	s_waitcnt lgkmcnt(7)
	v_mfma_f32_32x32x16_bf16 v[32:47], v[82:85], v[86:89], v[32:47]
	s_waitcnt lgkmcnt(6)
	v_mfma_f32_32x32x16_bf16 v[48:63], v[98:101], v[86:89], v[48:63]
	s_waitcnt lgkmcnt(4)
	v_mfma_f32_32x32x16_bf16 v[0:15], v[102:105], v[106:109], v[0:15]
	s_waitcnt lgkmcnt(3)
	v_mfma_f32_32x32x16_bf16 v[16:31], v[110:113], v[106:109], v[16:31]
	s_waitcnt lgkmcnt(1)
	v_mfma_f32_32x32x16_bf16 v[0:15], v[114:117], v[118:121], v[0:15]
	s_waitcnt lgkmcnt(0)
	v_mfma_f32_32x32x16_bf16 v[16:31], v[122:125], v[118:121], v[16:31]
	s_waitcnt vmcnt(2) lgkmcnt(0)
	s_barrier
	s_nop 11
	v_cvt_f32_ubyte0_e32 v184, v172
	s_cbranch_scc1 .LBB0_314
; #define ATT_DIAG_BIAS(s0, s1) do { const float dqh_ = dq - (float)(4 * hi); _Pragma("unroll") for (int r = 0; r < 16; ++r) { const float c_ = (float)((r & 3) + 8 * (r >> 2)); \
;         s0[r] = __builtin_fmaf(-sl, __builtin_fabsf(dqh_ - c_), s0[r]); s1[r] = __builtin_fmaf(-sl, __builtin_fabsf(dqh_ - (c_ + 32.f)), s1[r]); } } while (0)
;     ...
;       const bool diag = d0t == td; const float dq = (float)(tq - d0t * KVBLK);
;       if (ABL & 2) { asm volatile("" : "=v"(pa0), "=v"(pa1), "=v"(pa2), "=v"(pa3), "=v"(pb0), "=v"(pb1), "=v"(pb2), "=v"(pb3) : "v"(sa0), "v"(sa1), "v"(sb0), "v"(sb1)); } else {
;       if (diag) { ATT_DIAG_BIAS(sa0, sa1); ATT_DIAG_BIAS(sb0, sb1); }
	v_subrev_u32_e32 v64, s21, v171
	v_cvt_f32_i32_e32 v64, v64
	s_mov_b32 s26, 0xc2000000
	s_mov_b32 s27, 0xc2040000
	v_sub_f32_e32 v74, v64, v184
	v_pk_add_f32 v[64:65], v[74:75], s[26:27] op_sel_hi:[0,1]
	s_mov_b32 s26, -2.0
	s_mov_b32 s27, 0xc0400000
	v_pk_add_f32 v[76:77], v[74:75], s[26:27] op_sel_hi:[0,1]
	s_mov_b32 s26, 0xc2080000
	s_mov_b32 s27, 0xc20c0000
	v_pk_add_f32 v[78:79], v[74:75], s[26:27] op_sel_hi:[0,1]
	s_mov_b32 s26, 0xc1000000
	s_mov_b32 s27, 0xc1100000
	v_pk_add_f32 v[80:81], v[74:75], s[26:27] op_sel_hi:[0,1]
	s_mov_b32 s26, 0xc2200000
	s_mov_b32 s27, 0xc2240000
	v_pk_add_f32 v[82:83], v[74:75], s[26:27] op_sel_hi:[0,1]
	s_mov_b32 s26, 0xc1200000
	s_mov_b32 s27, 0xc1300000
	v_pk_add_f32 v[84:85], v[74:75], s[26:27] op_sel_hi:[0,1]
	s_mov_b32 s26, 0xc2280000
	s_mov_b32 s27, 0xc22c0000
	v_pk_add_f32 v[86:87], v[74:75], s[26:27] op_sel_hi:[0,1]
	s_mov_b32 s26, 0xc1800000
	s_mov_b32 s27, 0xc1880000
	v_pk_add_f32 v[88:89], v[74:75], s[26:27] op_sel_hi:[0,1]
	s_mov_b32 s26, 0xc2400000
	s_mov_b32 s27, 0xc2440000
	v_pk_add_f32 v[90:91], v[74:75], s[26:27] op_sel_hi:[0,1]
	s_mov_b32 s26, 0xc1900000
	s_mov_b32 s27, 0xc1980000
	v_pk_add_f32 v[98:99], v[74:75], s[26:27] op_sel_hi:[0,1]
	s_mov_b32 s26, 0xc2480000
	s_mov_b32 s27, 0xc24c0000
	v_pk_add_f32 v[100:101], v[74:75], s[26:27] op_sel_hi:[0,1]
	s_mov_b32 s26, 0xc1c00000
	s_mov_b32 s27, 0xc1c80000
	v_pk_add_f32 v[102:103], v[74:75], s[26:27] op_sel_hi:[0,1]
	s_mov_b32 s26, 0xc2600000
	s_mov_b32 s27, 0xc2640000
	v_pk_add_f32 v[104:105], v[74:75], s[26:27] op_sel_hi:[0,1]
	s_mov_b32 s26, 0xc1d00000
	s_mov_b32 s27, 0xc1d80000
	v_pk_add_f32 v[106:107], v[74:75], s[26:27] op_sel_hi:[0,1]
	s_mov_b32 s26, 0xc2680000
	s_mov_b32 s27, 0xc26c0000
	v_add_f32_e32 v73, -1.0, v74
	v_pk_add_f32 v[108:109], v[74:75], s[26:27] op_sel_hi:[0,1]
	v_and_b32_e32 v65, 0x7fffffff, v65
	v_and_b32_e32 v64, 0x7fffffff, v64
	v_and_b32_e32 v79, 0x7fffffff, v79
	v_and_b32_e32 v78, 0x7fffffff, v78
	v_and_b32_e32 v81, 0x7fffffff, v81
	v_and_b32_e32 v80, 0x7fffffff, v80
	v_and_b32_e32 v83, 0x7fffffff, v83
	v_and_b32_e32 v82, 0x7fffffff, v82
	v_and_b32_e32 v85, 0x7fffffff, v85
	v_and_b32_e32 v84, 0x7fffffff, v84
	v_and_b32_e32 v87, 0x7fffffff, v87
	v_and_b32_e32 v86, 0x7fffffff, v86
	v_and_b32_e32 v89, 0x7fffffff, v89
	v_and_b32_e32 v88, 0x7fffffff, v88
	v_and_b32_e32 v91, 0x7fffffff, v91
	v_and_b32_e32 v90, 0x7fffffff, v90
	v_and_b32_e32 v99, 0x7fffffff, v99
	v_and_b32_e32 v98, 0x7fffffff, v98
	v_and_b32_e32 v101, 0x7fffffff, v101
	v_and_b32_e32 v100, 0x7fffffff, v100
	v_and_b32_e32 v103, 0x7fffffff, v103
	v_and_b32_e32 v102, 0x7fffffff, v102
	v_and_b32_e32 v105, 0x7fffffff, v105
	v_and_b32_e32 v104, 0x7fffffff, v104
	v_and_b32_e32 v107, 0x7fffffff, v107
	v_and_b32_e32 v106, 0x7fffffff, v106
	v_and_b32_e32 v109, 0x7fffffff, v109
	v_and_b32_e32 v108, 0x7fffffff, v108
	v_and_b32_e32 v77, 0x7fffffff, v77
	v_and_b32_e32 v76, 0x7fffffff, v76
	v_and_b32_e32 v74, 0x7fffffff, v74
	v_and_b32_e32 v75, 0x7fffffff, v73
	v_pk_fma_f32 v[14:15], v[92:93], v[106:107], v[14:15] op_sel_hi:[0,1,1] neg_lo:[1,0,0] neg_hi:[1,0,0]
	v_pk_fma_f32 v[12:13], v[92:93], v[102:103], v[12:13] op_sel_hi:[0,1,1] neg_lo:[1,0,0] neg_hi:[1,0,0]
	v_pk_fma_f32 v[10:11], v[92:93], v[98:99], v[10:11] op_sel_hi:[0,1,1] neg_lo:[1,0,0] neg_hi:[1,0,0]
	v_pk_fma_f32 v[8:9], v[92:93], v[88:89], v[8:9] op_sel_hi:[0,1,1] neg_lo:[1,0,0] neg_hi:[1,0,0]
	v_pk_fma_f32 v[6:7], v[92:93], v[84:85], v[6:7] op_sel_hi:[0,1,1] neg_lo:[1,0,0] neg_hi:[1,0,0]
	v_pk_fma_f32 v[4:5], v[92:93], v[80:81], v[4:5] op_sel_hi:[0,1,1] neg_lo:[1,0,0] neg_hi:[1,0,0]
	v_pk_fma_f32 v[2:3], v[92:93], v[76:77], v[2:3] op_sel_hi:[0,1,1] neg_lo:[1,0,0] neg_hi:[1,0,0]
	v_pk_fma_f32 v[0:1], v[92:93], v[74:75], v[0:1] op_sel_hi:[0,1,1] neg_lo:[1,0,0] neg_hi:[1,0,0]
	v_pk_fma_f32 v[30:31], v[92:93], v[108:109], v[30:31] op_sel_hi:[0,1,1] neg_lo:[1,0,0] neg_hi:[1,0,0]
	v_pk_fma_f32 v[28:29], v[92:93], v[104:105], v[28:29] op_sel_hi:[0,1,1] neg_lo:[1,0,0] neg_hi:[1,0,0]
	v_pk_fma_f32 v[26:27], v[92:93], v[100:101], v[26:27] op_sel_hi:[0,1,1] neg_lo:[1,0,0] neg_hi:[1,0,0]
	v_pk_fma_f32 v[24:25], v[92:93], v[90:91], v[24:25] op_sel_hi:[0,1,1] neg_lo:[1,0,0] neg_hi:[1,0,0]
	v_pk_fma_f32 v[22:23], v[92:93], v[86:87], v[22:23] op_sel_hi:[0,1,1] neg_lo:[1,0,0] neg_hi:[1,0,0]
	v_pk_fma_f32 v[20:21], v[92:93], v[82:83], v[20:21] op_sel_hi:[0,1,1] neg_lo:[1,0,0] neg_hi:[1,0,0]
	v_pk_fma_f32 v[18:19], v[92:93], v[78:79], v[18:19] op_sel_hi:[0,1,1] neg_lo:[1,0,0] neg_hi:[1,0,0]
	v_pk_fma_f32 v[16:17], v[92:93], v[64:65], v[16:17] op_sel_hi:[0,1,1] neg_lo:[1,0,0] neg_hi:[1,0,0]
	v_pk_fma_f32 v[46:47], v[92:93], v[106:107], v[46:47] op_sel_hi:[0,1,1] neg_lo:[1,0,0] neg_hi:[1,0,0]
	v_pk_fma_f32 v[44:45], v[92:93], v[102:103], v[44:45] op_sel_hi:[0,1,1] neg_lo:[1,0,0] neg_hi:[1,0,0]
	v_pk_fma_f32 v[42:43], v[92:93], v[98:99], v[42:43] op_sel_hi:[0,1,1] neg_lo:[1,0,0] neg_hi:[1,0,0]
	v_pk_fma_f32 v[40:41], v[92:93], v[88:89], v[40:41] op_sel_hi:[0,1,1] neg_lo:[1,0,0] neg_hi:[1,0,0]
	v_pk_fma_f32 v[38:39], v[92:93], v[84:85], v[38:39] op_sel_hi:[0,1,1] neg_lo:[1,0,0] neg_hi:[1,0,0]
	v_pk_fma_f32 v[36:37], v[92:93], v[80:81], v[36:37] op_sel_hi:[0,1,1] neg_lo:[1,0,0] neg_hi:[1,0,0]
	v_pk_fma_f32 v[34:35], v[92:93], v[76:77], v[34:35] op_sel_hi:[0,1,1] neg_lo:[1,0,0] neg_hi:[1,0,0]
	v_pk_fma_f32 v[32:33], v[92:93], v[74:75], v[32:33] op_sel_hi:[0,1,1] neg_lo:[1,0,0] neg_hi:[1,0,0]
	v_pk_fma_f32 v[62:63], v[92:93], v[108:109], v[62:63] op_sel_hi:[0,1,1] neg_lo:[1,0,0] neg_hi:[1,0,0]
	v_pk_fma_f32 v[60:61], v[92:93], v[104:105], v[60:61] op_sel_hi:[0,1,1] neg_lo:[1,0,0] neg_hi:[1,0,0]
	v_pk_fma_f32 v[58:59], v[92:93], v[100:101], v[58:59] op_sel_hi:[0,1,1] neg_lo:[1,0,0] neg_hi:[1,0,0]
	v_pk_fma_f32 v[56:57], v[92:93], v[90:91], v[56:57] op_sel_hi:[0,1,1] neg_lo:[1,0,0] neg_hi:[1,0,0]
	v_pk_fma_f32 v[54:55], v[92:93], v[86:87], v[54:55] op_sel_hi:[0,1,1] neg_lo:[1,0,0] neg_hi:[1,0,0]
	v_pk_fma_f32 v[52:53], v[92:93], v[82:83], v[52:53] op_sel_hi:[0,1,1] neg_lo:[1,0,0] neg_hi:[1,0,0]
	v_pk_fma_f32 v[50:51], v[92:93], v[78:79], v[50:51] op_sel_hi:[0,1,1] neg_lo:[1,0,0] neg_hi:[1,0,0]
	v_pk_fma_f32 v[48:49], v[92:93], v[64:65], v[48:49] op_sel_hi:[0,1,1] neg_lo:[1,0,0] neg_hi:[1,0,0]
